# MF3 GEMM loops: waves 4-7 mask surplus A-row LDS-DMA piece to lane 0
# speedup vs baseline: 1.0120x; 1.0120x over previous
_Z14fwd_megakernel6Params:
	v_readfirstlane_b32 s98, v0
	s_bfe_u32 s98, s98, 0x40006
	s_cmp_ge_u32 s98, 4
	s_cselect_b64 s[98:99], 1, -1
	s_load_dwordx4 s[36:39], s[0:1], 0xc0
	s_mov_b64 s[88:89], s[0:1]
	s_add_u32 s4, s88, 0xc8
	s_addc_u32 s5, s89, 0
	s_mov_b32 s56, s2
	s_waitcnt lgkmcnt(0)
	s_cmp_lt_i32 s36, 0
	s_cbranch_scc1 .LBB0_2
	v_and_b32_e32 v204, 0x3ff, v0
	s_load_dwordx2 s[0:1], s[88:89], 0xb8
	s_load_dword s34, s[88:89], 0xd0
	s_cbranch_execz .LBB0_3
	s_branch .LBB0_14

.LBB0_384:
	s_add_u32 s54, s42, 0xfffd0080
	s_addc_u32 s55, s43, -1
	s_add_i32 s70, 0, 0x10000
	v_add_u32_e32 v96, s70, v157
	ds_read_b128 v[160:163], v96
	ds_read_b128 v[164:167], v96 offset:1024
	ds_read_b128 v[168:171], v96 offset:2048
	ds_read_b128 v[172:175], v96 offset:3072
	s_cmp_eq_u32 s69, 12
	s_cselect_b32 s57, s51, s55
	s_cselect_b32 s56, s50, s54
	s_cselect_b32 s55, s49, s68
	s_cselect_b32 s54, s66, s67
	v_lshl_add_u64 v[154:155], s[42:43], 0, v[150:151]
	s_add_i32 m0, s28, 0xc000
	ds_read_b128 v[182:185], v159
	ds_read_b128 v[186:189], v159 offset:1024
	ds_read_b128 v[190:193], v159 offset:2048
	ds_read_b128 v[194:197], v159 offset:3072
	ds_read_b128 v[198:201], v159 offset:4096
	ds_read_b128 v[224:227], v159 offset:5120
	global_load_lds_dwordx4 v[154:155], off
	v_lshl_add_u64 v[154:155], s[42:43], 0, v[152:153]
	s_add_i32 m0, s28, 0xe000
	s_mov_b64 exec, s[98:99]
	global_load_lds_dwordx4 v[154:155], off
	s_mov_b64 exec, -1
	s_waitcnt lgkmcnt(8)
	s_barrier
	s_waitcnt lgkmcnt(0)
	s_setprio 1
	s_waitcnt lgkmcnt(0)
	v_mfma_f32_16x16x32_bf16 v[134:137], v[160:163], v[182:185], v[134:137]
	v_mfma_f32_16x16x32_bf16 v[130:133], v[168:171], v[182:185], v[130:133]
	v_mfma_f32_16x16x32_bf16 v[118:121], v[160:163], v[190:193], v[118:121]
	v_mfma_f32_16x16x32_bf16 v[114:117], v[168:171], v[190:193], v[114:117]
	v_mfma_f32_16x16x32_bf16 v[102:105], v[160:163], v[198:201], v[102:105]
	v_mfma_f32_16x16x32_bf16 v[98:101], v[168:171], v[198:201], v[98:101]
	v_mfma_f32_16x16x32_bf16 v[134:137], v[164:167], v[186:189], v[134:137]
	v_mfma_f32_16x16x32_bf16 v[130:133], v[172:175], v[186:189], v[130:133]
	v_mfma_f32_16x16x32_bf16 v[118:121], v[164:167], v[194:197], v[118:121]
	v_mfma_f32_16x16x32_bf16 v[114:117], v[172:175], v[194:197], v[114:117]
	v_mfma_f32_16x16x32_bf16 v[102:105], v[164:167], v[224:227], v[102:105]
	v_mfma_f32_16x16x32_bf16 v[98:101], v[172:175], v[224:227], v[98:101]
	s_setprio 0
	s_barrier
	s_add_i32 s72, 0, 0x14000
	s_add_i32 s70, s70, s18
	v_add_u32_e32 v96, s72, v157
	v_lshl_add_u64 v[154:155], s[54:55], 0, v[142:143]
	s_mov_b32 m0, s70
	ds_read_b128 v[228:231], v96
	ds_read_b128 v[232:235], v96 offset:1024
	ds_read_b128 v[236:239], v96 offset:2048
	ds_read_b128 v[240:243], v96 offset:3072
	global_load_lds_dwordx4 v[154:155], off
	v_lshl_add_u64 v[176:177], s[54:55], 0, v[138:139]
	s_add_i32 m0, s70, 0x2000
	s_nop 0
	global_load_lds_dwordx4 v[176:177], off
	s_barrier
	s_waitcnt lgkmcnt(0)
	s_setprio 1
	s_waitcnt lgkmcnt(0)
	v_mfma_f32_16x16x32_bf16 v[126:129], v[228:231], v[182:185], v[126:129]
	v_mfma_f32_16x16x32_bf16 v[122:125], v[236:239], v[182:185], v[122:125]
	v_mfma_f32_16x16x32_bf16 v[110:113], v[228:231], v[190:193], v[110:113]
	v_mfma_f32_16x16x32_bf16 v[106:109], v[236:239], v[190:193], v[106:109]
	v_mfma_f32_16x16x32_bf16 v[92:95], v[228:231], v[198:201], v[92:95]
	v_mfma_f32_16x16x32_bf16 v[88:91], v[236:239], v[198:201], v[88:91]
	v_mfma_f32_16x16x32_bf16 v[126:129], v[232:235], v[186:189], v[126:129]
	v_mfma_f32_16x16x32_bf16 v[122:125], v[240:243], v[186:189], v[122:125]
	v_mfma_f32_16x16x32_bf16 v[110:113], v[232:235], v[194:197], v[110:113]
	v_mfma_f32_16x16x32_bf16 v[106:109], v[240:243], v[194:197], v[106:109]
	v_mfma_f32_16x16x32_bf16 v[92:95], v[232:235], v[224:227], v[92:95]
	v_mfma_f32_16x16x32_bf16 v[88:91], v[240:243], v[224:227], v[88:91]
	s_setprio 0
	s_mov_b32 m0, s28
	v_lshl_add_u64 v[202:203], s[56:57], 0, v[144:145]
	s_barrier
	ds_read_b128 v[182:185], v159 offset:16384
	ds_read_b128 v[186:189], v159 offset:17408
	ds_read_b128 v[190:193], v159 offset:18432
	ds_read_b128 v[194:197], v159 offset:19456
	ds_read_b128 v[198:201], v159 offset:20480
	ds_read_b128 v[224:227], v159 offset:21504
	global_load_lds_dwordx4 v[202:203], off
	v_lshl_add_u64 v[244:245], s[56:57], 0, v[140:141]
	s_mov_b32 m0, s37
	s_mov_b64 exec, s[98:99]
	global_load_lds_dwordx4 v[244:245], off
	s_mov_b64 exec, -1
	s_barrier
	s_waitcnt lgkmcnt(0)
	s_setprio 1
	s_waitcnt lgkmcnt(0)
	v_mfma_f32_16x16x32_bf16 v[84:87], v[160:163], v[182:185], v[84:87]
	v_mfma_f32_16x16x32_bf16 v[80:83], v[168:171], v[182:185], v[80:83]
	v_mfma_f32_16x16x32_bf16 v[68:71], v[160:163], v[190:193], v[68:71]
	v_mfma_f32_16x16x32_bf16 v[64:67], v[168:171], v[190:193], v[64:67]
	v_mfma_f32_16x16x32_bf16 v[28:31], v[160:163], v[198:201], v[28:31]
	v_mfma_f32_16x16x32_bf16 v[24:27], v[168:171], v[198:201], v[24:27]
	v_mfma_f32_16x16x32_bf16 v[84:87], v[164:167], v[186:189], v[84:87]
	v_mfma_f32_16x16x32_bf16 v[80:83], v[172:175], v[186:189], v[80:83]
	v_mfma_f32_16x16x32_bf16 v[68:71], v[164:167], v[194:197], v[68:71]
	v_mfma_f32_16x16x32_bf16 v[64:67], v[172:175], v[194:197], v[64:67]
	v_mfma_f32_16x16x32_bf16 v[28:31], v[164:167], v[224:227], v[28:31]
	v_mfma_f32_16x16x32_bf16 v[24:27], v[172:175], v[224:227], v[24:27]
	s_setprio 0
	s_barrier
	s_add_u32 s70, s54, 0x40000
	s_addc_u32 s71, s55, 0
	s_add_i32 s72, s72, s18
	v_lshl_add_u64 v[160:161], s[70:71], 0, v[142:143]
	s_mov_b32 m0, s72
	s_nop 0
	global_load_lds_dwordx4 v[160:161], off
	v_lshl_add_u64 v[160:161], s[70:71], 0, v[138:139]
	s_add_i32 m0, s72, 0x2000
	s_nop 0
	global_load_lds_dwordx4 v[160:161], off
	s_waitcnt vmcnt(6)
	s_barrier
	s_setprio 1
	v_mfma_f32_16x16x32_bf16 v[76:79], v[228:231], v[182:185], v[76:79]
	v_mfma_f32_16x16x32_bf16 v[72:75], v[236:239], v[182:185], v[72:75]
	v_mfma_f32_16x16x32_bf16 v[60:63], v[228:231], v[190:193], v[60:63]
	v_mfma_f32_16x16x32_bf16 v[56:59], v[236:239], v[190:193], v[56:59]
	v_mfma_f32_16x16x32_bf16 v[20:23], v[228:231], v[198:201], v[20:23]
	v_mfma_f32_16x16x32_bf16 v[16:19], v[236:239], v[198:201], v[16:19]
	v_mfma_f32_16x16x32_bf16 v[76:79], v[232:235], v[186:189], v[76:79]
	v_mfma_f32_16x16x32_bf16 v[72:75], v[240:243], v[186:189], v[72:75]
	v_mfma_f32_16x16x32_bf16 v[60:63], v[232:235], v[194:197], v[60:63]
	v_mfma_f32_16x16x32_bf16 v[56:59], v[240:243], v[194:197], v[56:59]
	v_mfma_f32_16x16x32_bf16 v[20:23], v[232:235], v[224:227], v[20:23]
	v_mfma_f32_16x16x32_bf16 v[16:19], v[240:243], v[224:227], v[16:19]
	s_setprio 0
	s_add_i32 s70, 0, 0x18000
	v_add_u32_e32 v96, s70, v157
	s_barrier
	ds_read_b128 v[160:163], v96
	ds_read_b128 v[164:167], v96 offset:1024
	ds_read_b128 v[168:171], v96 offset:2048
	ds_read_b128 v[172:175], v96 offset:3072
	s_add_u32 s56, s56, 0x30000
	s_addc_u32 s57, s57, 0
	s_mov_b32 m0, s58
	v_lshl_add_u64 v[228:229], s[56:57], 0, v[144:145]
	ds_read_b128 v[182:185], v159 offset:32768
	ds_read_b128 v[186:189], v159 offset:33792
	ds_read_b128 v[190:193], v159 offset:34816
	ds_read_b128 v[194:197], v159 offset:35840
	ds_read_b128 v[198:201], v159 offset:36864
	ds_read_b128 v[224:227], v159 offset:37888
	global_load_lds_dwordx4 v[228:229], off
	v_lshl_add_u64 v[228:229], s[56:57], 0, v[140:141]
	s_mov_b32 m0, s59
	s_mov_b64 exec, s[98:99]
	global_load_lds_dwordx4 v[228:229], off
	s_mov_b64 exec, -1
	s_waitcnt lgkmcnt(8)
	s_barrier
	s_waitcnt lgkmcnt(0)
	s_setprio 1
	s_waitcnt lgkmcnt(0)
	v_mfma_f32_16x16x32_bf16 v[134:137], v[160:163], v[182:185], v[134:137]
	v_mfma_f32_16x16x32_bf16 v[130:133], v[168:171], v[182:185], v[130:133]
	v_mfma_f32_16x16x32_bf16 v[118:121], v[160:163], v[190:193], v[118:121]
	v_mfma_f32_16x16x32_bf16 v[114:117], v[168:171], v[190:193], v[114:117]
	v_mfma_f32_16x16x32_bf16 v[102:105], v[160:163], v[198:201], v[102:105]
	v_mfma_f32_16x16x32_bf16 v[98:101], v[168:171], v[198:201], v[98:101]
	v_mfma_f32_16x16x32_bf16 v[134:137], v[164:167], v[186:189], v[134:137]
	v_mfma_f32_16x16x32_bf16 v[130:133], v[172:175], v[186:189], v[130:133]
	v_mfma_f32_16x16x32_bf16 v[118:121], v[164:167], v[194:197], v[118:121]
	v_mfma_f32_16x16x32_bf16 v[114:117], v[172:175], v[194:197], v[114:117]
	v_mfma_f32_16x16x32_bf16 v[102:105], v[164:167], v[224:227], v[102:105]
	v_mfma_f32_16x16x32_bf16 v[98:101], v[172:175], v[224:227], v[98:101]
	s_setprio 0
	s_barrier
	s_add_i32 s56, 0, 0x1c000
	s_add_i32 s57, s70, s18
	v_add_u32_e32 v96, s56, v157
	v_lshl_add_u64 v[154:155], v[154:155], 0, s[6:7]
	s_mov_b32 m0, s57
	ds_read_b128 v[228:231], v96
	ds_read_b128 v[232:235], v96 offset:1024
	ds_read_b128 v[236:239], v96 offset:2048
	ds_read_b128 v[240:243], v96 offset:3072
	global_load_lds_dwordx4 v[154:155], off
	v_lshl_add_u64 v[154:155], v[176:177], 0, s[6:7]
	s_add_i32 m0, s57, 0x2000
	s_nop 0
	global_load_lds_dwordx4 v[154:155], off
	s_barrier
	s_waitcnt lgkmcnt(0)
	s_setprio 1
	s_waitcnt lgkmcnt(0)
	v_mfma_f32_16x16x32_bf16 v[126:129], v[228:231], v[182:185], v[126:129]
	v_mfma_f32_16x16x32_bf16 v[122:125], v[236:239], v[182:185], v[122:125]
	v_mfma_f32_16x16x32_bf16 v[110:113], v[228:231], v[190:193], v[110:113]
	v_mfma_f32_16x16x32_bf16 v[106:109], v[236:239], v[190:193], v[106:109]
	v_mfma_f32_16x16x32_bf16 v[92:95], v[228:231], v[198:201], v[92:95]
	v_mfma_f32_16x16x32_bf16 v[88:91], v[236:239], v[198:201], v[88:91]
	v_mfma_f32_16x16x32_bf16 v[126:129], v[232:235], v[186:189], v[126:129]
	v_mfma_f32_16x16x32_bf16 v[122:125], v[240:243], v[186:189], v[122:125]
	v_mfma_f32_16x16x32_bf16 v[110:113], v[232:235], v[194:197], v[110:113]
	v_mfma_f32_16x16x32_bf16 v[106:109], v[240:243], v[194:197], v[106:109]
	v_mfma_f32_16x16x32_bf16 v[92:95], v[232:235], v[224:227], v[92:95]
	v_mfma_f32_16x16x32_bf16 v[88:91], v[240:243], v[224:227], v[88:91]
	s_setprio 0
	s_mov_b32 m0, s60
	v_lshl_add_u64 v[154:155], v[202:203], 0, s[6:7]
	s_barrier
	ds_read_b128 v[182:185], v159 offset:49152
	ds_read_b128 v[186:189], v159 offset:50176
	ds_read_b128 v[190:193], v159 offset:51200
	ds_read_b128 v[194:197], v159 offset:52224
	ds_read_b128 v[198:201], v159 offset:53248
	ds_read_b128 v[224:227], v159 offset:54272
	global_load_lds_dwordx4 v[154:155], off
	v_lshl_add_u64 v[154:155], v[244:245], 0, s[6:7]
	s_mov_b32 m0, s61
	s_mov_b64 exec, s[98:99]
	global_load_lds_dwordx4 v[154:155], off
	s_mov_b64 exec, -1
	s_barrier
	s_waitcnt lgkmcnt(0)
	s_setprio 1
	s_waitcnt lgkmcnt(0)
	v_mfma_f32_16x16x32_bf16 v[84:87], v[160:163], v[182:185], v[84:87]
	v_mfma_f32_16x16x32_bf16 v[80:83], v[168:171], v[182:185], v[80:83]
	v_mfma_f32_16x16x32_bf16 v[68:71], v[160:163], v[190:193], v[68:71]
	v_mfma_f32_16x16x32_bf16 v[64:67], v[168:171], v[190:193], v[64:67]
	v_mfma_f32_16x16x32_bf16 v[28:31], v[160:163], v[198:201], v[28:31]
	v_mfma_f32_16x16x32_bf16 v[24:27], v[168:171], v[198:201], v[24:27]
	v_mfma_f32_16x16x32_bf16 v[84:87], v[164:167], v[186:189], v[84:87]
	v_mfma_f32_16x16x32_bf16 v[80:83], v[172:175], v[186:189], v[80:83]
	v_mfma_f32_16x16x32_bf16 v[68:71], v[164:167], v[194:197], v[68:71]
	v_mfma_f32_16x16x32_bf16 v[64:67], v[172:175], v[194:197], v[64:67]
	v_mfma_f32_16x16x32_bf16 v[28:31], v[164:167], v[224:227], v[28:31]
	v_mfma_f32_16x16x32_bf16 v[24:27], v[172:175], v[224:227], v[24:27]
	s_setprio 0
	s_barrier
	s_add_u32 s54, s54, 0x40080
	s_addc_u32 s55, s55, 0
	s_add_i32 s56, s56, s18
	v_lshl_add_u64 v[154:155], s[54:55], 0, v[142:143]
	s_mov_b32 m0, s56
	s_nop 0
	global_load_lds_dwordx4 v[154:155], off
	v_lshl_add_u64 v[154:155], s[54:55], 0, v[138:139]
	s_add_i32 m0, s56, 0x2000
	s_nop 0
	global_load_lds_dwordx4 v[154:155], off
	s_waitcnt vmcnt(6)
	s_barrier
	s_setprio 1
	v_mfma_f32_16x16x32_bf16 v[76:79], v[228:231], v[182:185], v[76:79]
	v_mfma_f32_16x16x32_bf16 v[72:75], v[236:239], v[182:185], v[72:75]
	v_mfma_f32_16x16x32_bf16 v[60:63], v[228:231], v[190:193], v[60:63]
	v_mfma_f32_16x16x32_bf16 v[56:59], v[236:239], v[190:193], v[56:59]
	v_mfma_f32_16x16x32_bf16 v[20:23], v[228:231], v[198:201], v[20:23]
	v_mfma_f32_16x16x32_bf16 v[16:19], v[236:239], v[198:201], v[16:19]
	v_mfma_f32_16x16x32_bf16 v[76:79], v[232:235], v[186:189], v[76:79]
	v_mfma_f32_16x16x32_bf16 v[72:75], v[240:243], v[186:189], v[72:75]
	v_mfma_f32_16x16x32_bf16 v[60:63], v[232:235], v[194:197], v[60:63]
	v_mfma_f32_16x16x32_bf16 v[56:59], v[240:243], v[194:197], v[56:59]
	v_mfma_f32_16x16x32_bf16 v[20:23], v[232:235], v[224:227], v[20:23]
	v_mfma_f32_16x16x32_bf16 v[16:19], v[240:243], v[224:227], v[16:19]
	s_setprio 0
	s_add_i32 s69, s69, 2
	s_add_u32 s42, s42, 0x100
	s_addc_u32 s43, s43, 0
	s_add_u32 s67, s67, 0x100
	s_addc_u32 s68, s68, 0
	s_cmp_gt_u32 s69, 13
	s_barrier
	s_cbranch_scc0 .LBB0_384
	s_waitcnt vmcnt(0)
	v_add_f32_e32 v52, v52, v53
	v_add_f32_e32 v53, v54, v55
	v_add_f32_e32 v52, v52, v53
	v_mov_b32_e32 v53, v52
	s_nop 1
	v_permlane16_swap_b32_e32 v52, v53
	v_add_f32_e32 v52, v52, v53
	v_mov_b32_e32 v53, v52
	s_nop 1
	v_permlane32_swap_b32_e32 v52, v53
	v_add_f32_e32 v52, v52, v53
	v_fmamk_f32 v52, v52, 0x3a800000, v207
	s_mul_i32 s42, s65, 0xc0
	v_rsq_f32_e32 v52, v52
	v_add_f32_e32 v36, v36, v37
	v_add_f32_e32 v37, v38, v39
	s_add_i32 s42, s42, s19
	v_add_f32_e32 v44, v44, v45
	v_add_f32_e32 v45, v46, v47
	v_add_f32_e32 v36, v36, v37
	s_cmpk_lt_u32 s42, 0x2000
	v_add_f32_e32 v44, v44, v45
	v_mov_b32_e32 v37, v36
	v_lshl_or_b32 v154, s64, 8, v158
	s_cselect_b32 s43, 1, 2
	v_or_b32_e32 v160, s42, v156
	v_mov_b32_e32 v45, v44
	v_permlane16_swap_b32_e32 v36, v37
	v_add_f32_e32 v32, v32, v33
	v_add_f32_e32 v33, v34, v35
	v_mov_b64_e32 v[34:35], s[46:47]
	v_mov_b32_e32 v96, s43
	v_permlane16_swap_b32_e32 v44, v45
	v_add_f32_e32 v38, v36, v37
	v_add_f32_e32 v36, v40, v41
	v_add_f32_e32 v37, v42, v43
	v_ashrrev_i32_e32 v155, 31, v154
	v_mad_i64_i32 v[34:35], s[42:43], v160, s25, v[34:35]
	v_pk_fma_f32 v[42:43], v[136:137], v[52:53], v[6:7] op_sel_hi:[1,0,1]
	v_pk_fma_f32 v[40:41], v[134:135], v[52:53], v[4:5] op_sel_hi:[1,0,1]
	v_add_f32_e32 v46, v44, v45
	v_add_f32_e32 v44, v48, v49
	v_add_f32_e32 v45, v50, v51
	v_lshl_add_u64 v[34:35], v[154:155], 1, v[34:35]
	v_pk_fma_f32 v[48:49], v[132:133], v[52:53], v[2:3] op_sel_hi:[1,0,1]
	v_pk_fma_f32 v[50:51], v[130:131], v[52:53], v[0:1] op_sel_hi:[1,0,1]
	v_cvt_pk_bf16_f32 v40, v40, v41
	v_cvt_pk_bf16_f32 v41, v42, v43
	v_add_f32_e32 v44, v44, v45
	v_cvt_pk_bf16_f32 v42, v50, v51
	v_cvt_pk_bf16_f32 v43, v48, v49
	v_add_f32_e32 v36, v36, v37
	v_add_f32_e32 v32, v32, v33
	global_store_dwordx4 v[34:35], v[40:43], off
	v_cmp_lt_i32_e32 vcc, s23, v160
	v_mov_b32_e32 v45, v44
	v_pk_fma_f32 v[42:43], v[128:129], v[52:53], v[14:15] op_sel_hi:[1,0,1]
	v_pk_fma_f32 v[40:41], v[126:127], v[52:53], v[12:13] op_sel_hi:[1,0,1]
	v_mov_b32_e32 v37, v36
	v_mov_b32_e32 v33, v32
	v_pk_fma_f32 v[48:49], v[124:125], v[52:53], v[10:11] op_sel_hi:[1,0,1]
	v_pk_fma_f32 v[50:51], v[122:123], v[52:53], v[8:9] op_sel_hi:[1,0,1]
	v_cvt_pk_bf16_f32 v40, v40, v41
	v_cvt_pk_bf16_f32 v41, v42, v43
	v_cndmask_b32_e32 v96, 0, v96, vcc
	v_cvt_pk_bf16_f32 v42, v50, v51
	v_cvt_pk_bf16_f32 v43, v48, v49
	global_store_dwordx4 v[34:35], v[40:43], off offset:256
	v_add_u32_e32 v34, 16, v160
	v_permlane16_swap_b32_e32 v44, v45
	v_permlane16_swap_b32_e32 v36, v37
	v_permlane16_swap_b32_e32 v32, v33
	v_cmp_gt_u32_e32 vcc, s24, v34
	v_add_f32_e32 v44, v44, v45
	v_add_f32_e32 v36, v36, v37
	v_add_f32_e32 v32, v32, v33
	v_cndmask_b32_e64 v35, 2, 1, vcc
	v_cmp_lt_i32_e32 vcc, s26, v160
	v_mov_b32_e32 v47, v46
	v_mov_b32_e32 v45, v44
	v_mov_b32_e32 v39, v38
	v_mov_b32_e32 v37, v36
	v_mov_b32_e32 v33, v32
	v_cndmask_b32_e32 v35, 0, v35, vcc
	v_permlane32_swap_b32_e32 v46, v47
	v_permlane32_swap_b32_e32 v44, v45
	v_permlane32_swap_b32_e32 v38, v39
	v_permlane32_swap_b32_e32 v36, v37
	v_permlane32_swap_b32_e32 v32, v33
	v_cmp_ne_u32_e32 vcc, v35, v96
	s_and_saveexec_b64 s[42:43], vcc
	s_cbranch_execz .LBB0_387
	v_mul_u32_u24_e32 v0, 0x7600, v35
	v_lshlrev_b32_e32 v96, 2, v0
	v_lshl_add_u64 v[0:1], s[44:45], 0, v[96:97]
	v_lshl_add_u64 v[12:13], v[154:155], 2, v[0:1]
	global_load_dwordx4 v[0:3], v[12:13], off offset:16
	global_load_dwordx4 v[4:7], v[12:13], off
	global_load_dwordx4 v[8:11], v[12:13], off offset:528
	s_nop 0
	global_load_dwordx4 v[12:15], v[12:13], off offset:512
	v_mov_b32_e32 v96, v35

.LBB0_465:
	s_add_u32 s58, s42, 0xfffd0080
	s_addc_u32 s59, s43, -1
	s_add_i32 s72, 0, 0x10000
	v_add_u32_e32 v96, s72, v163
	ds_read_b128 v[154:157], v96
	ds_read_b128 v[170:173], v96 offset:1024
	ds_read_b128 v[174:177], v96 offset:2048
	ds_read_b128 v[182:185], v96 offset:3072
	s_cmp_eq_u32 s71, 12
	s_cselect_b32 s61, s53, s59
	s_cselect_b32 s60, s52, s58
	s_cselect_b32 s59, s51, s70
	s_cselect_b32 s58, s68, s69
	v_lshl_add_u64 v[160:161], s[42:43], 0, v[150:151]
	s_add_i32 m0, s27, 0xc000
	ds_read_b128 v[186:189], v168
	ds_read_b128 v[190:193], v168 offset:1024
	ds_read_b128 v[194:197], v168 offset:2048
	ds_read_b128 v[198:201], v168 offset:3072
	ds_read_b128 v[224:227], v168 offset:4096
	ds_read_b128 v[228:231], v168 offset:5120
	global_load_lds_dwordx4 v[160:161], off
	v_lshl_add_u64 v[160:161], s[42:43], 0, v[152:153]
	s_add_i32 m0, s27, 0xe000
	s_mov_b64 exec, s[98:99]
	global_load_lds_dwordx4 v[160:161], off
	s_mov_b64 exec, -1
	s_waitcnt lgkmcnt(8)
	s_barrier
	s_waitcnt lgkmcnt(0)
	s_setprio 1
	s_waitcnt lgkmcnt(0)
	v_mfma_f32_16x16x32_bf16 v[134:137], v[154:157], v[186:189], v[134:137]
	v_mfma_f32_16x16x32_bf16 v[130:133], v[174:177], v[186:189], v[130:133]
	v_mfma_f32_16x16x32_bf16 v[92:95], v[154:157], v[194:197], v[92:95]
	v_mfma_f32_16x16x32_bf16 v[88:91], v[174:177], v[194:197], v[88:91]
	v_mfma_f32_16x16x32_bf16 v[76:79], v[154:157], v[224:227], v[76:79]
	v_mfma_f32_16x16x32_bf16 v[72:75], v[174:177], v[224:227], v[72:75]
	v_mfma_f32_16x16x32_bf16 v[134:137], v[170:173], v[190:193], v[134:137]
	v_mfma_f32_16x16x32_bf16 v[130:133], v[182:185], v[190:193], v[130:133]
	v_mfma_f32_16x16x32_bf16 v[92:95], v[170:173], v[198:201], v[92:95]
	v_mfma_f32_16x16x32_bf16 v[88:91], v[182:185], v[198:201], v[88:91]
	v_mfma_f32_16x16x32_bf16 v[76:79], v[170:173], v[228:231], v[76:79]
	v_mfma_f32_16x16x32_bf16 v[72:75], v[182:185], v[228:231], v[72:75]
	s_setprio 0
	s_barrier
	s_add_i32 s80, 0, 0x14000
	s_add_i32 s72, s72, s18
	v_add_u32_e32 v96, s80, v163
	v_lshl_add_u64 v[160:161], s[58:59], 0, v[140:141]
	s_mov_b32 m0, s72
	ds_read_b128 v[232:235], v96
	ds_read_b128 v[236:239], v96 offset:1024
	ds_read_b128 v[240:243], v96 offset:2048
	ds_read_b128 v[244:247], v96 offset:3072
	global_load_lds_dwordx4 v[160:161], off
	v_lshl_add_u64 v[164:165], s[58:59], 0, v[144:145]
	s_add_i32 m0, s72, 0x2000
	s_nop 0
	global_load_lds_dwordx4 v[164:165], off
	s_barrier
	s_waitcnt lgkmcnt(0)
	s_setprio 1
	s_waitcnt lgkmcnt(0)
	v_mfma_f32_16x16x32_bf16 v[110:113], v[232:235], v[186:189], v[110:113]
	v_mfma_f32_16x16x32_bf16 v[98:101], v[240:243], v[186:189], v[98:101]
	v_mfma_f32_16x16x32_bf16 v[84:87], v[232:235], v[194:197], v[84:87]
	v_mfma_f32_16x16x32_bf16 v[80:83], v[240:243], v[194:197], v[80:83]
	v_mfma_f32_16x16x32_bf16 v[68:71], v[232:235], v[224:227], v[68:71]
	v_mfma_f32_16x16x32_bf16 v[64:67], v[240:243], v[224:227], v[64:67]
	v_mfma_f32_16x16x32_bf16 v[110:113], v[236:239], v[190:193], v[110:113]
	v_mfma_f32_16x16x32_bf16 v[98:101], v[244:247], v[190:193], v[98:101]
	v_mfma_f32_16x16x32_bf16 v[84:87], v[236:239], v[198:201], v[84:87]
	v_mfma_f32_16x16x32_bf16 v[80:83], v[244:247], v[198:201], v[80:83]
	v_mfma_f32_16x16x32_bf16 v[68:71], v[236:239], v[228:231], v[68:71]
	v_mfma_f32_16x16x32_bf16 v[64:67], v[244:247], v[228:231], v[64:67]
	s_setprio 0
	s_mov_b32 m0, s27
	v_lshl_add_u64 v[202:203], s[60:61], 0, v[138:139]
	s_barrier
	ds_read_b128 v[186:189], v168 offset:16384
	ds_read_b128 v[190:193], v168 offset:17408
	ds_read_b128 v[194:197], v168 offset:18432
	ds_read_b128 v[198:201], v168 offset:19456
	ds_read_b128 v[224:227], v168 offset:20480
	ds_read_b128 v[228:231], v168 offset:21504
	global_load_lds_dwordx4 v[202:203], off
	v_lshl_add_u64 v[248:249], s[60:61], 0, v[142:143]
	s_mov_b32 m0, s28
	s_mov_b64 exec, s[98:99]
	global_load_lds_dwordx4 v[248:249], off
	s_mov_b64 exec, -1
	s_barrier
	s_waitcnt lgkmcnt(0)
	s_setprio 1
	s_waitcnt lgkmcnt(0)
	v_mfma_f32_16x16x32_bf16 v[60:63], v[154:157], v[186:189], v[60:63]
	v_mfma_f32_16x16x32_bf16 v[56:59], v[174:177], v[186:189], v[56:59]
	v_mfma_f32_16x16x32_bf16 v[44:47], v[154:157], v[194:197], v[44:47]
	v_mfma_f32_16x16x32_bf16 v[40:43], v[174:177], v[194:197], v[40:43]
	v_mfma_f32_16x16x32_bf16 v[28:31], v[154:157], v[224:227], v[28:31]
	v_mfma_f32_16x16x32_bf16 v[24:27], v[174:177], v[224:227], v[24:27]
	v_mfma_f32_16x16x32_bf16 v[60:63], v[170:173], v[190:193], v[60:63]
	v_mfma_f32_16x16x32_bf16 v[56:59], v[182:185], v[190:193], v[56:59]
	v_mfma_f32_16x16x32_bf16 v[44:47], v[170:173], v[198:201], v[44:47]
	v_mfma_f32_16x16x32_bf16 v[40:43], v[182:185], v[198:201], v[40:43]
	v_mfma_f32_16x16x32_bf16 v[28:31], v[170:173], v[228:231], v[28:31]
	v_mfma_f32_16x16x32_bf16 v[24:27], v[182:185], v[228:231], v[24:27]
	s_setprio 0
	s_barrier
	s_add_u32 s78, s58, 0x40000
	s_addc_u32 s79, s59, 0
	s_add_i32 s72, s80, s18
	v_lshl_add_u64 v[154:155], s[78:79], 0, v[140:141]
	s_mov_b32 m0, s72
	s_nop 0
	global_load_lds_dwordx4 v[154:155], off
	v_lshl_add_u64 v[154:155], s[78:79], 0, v[144:145]
	s_add_i32 m0, s72, 0x2000
	s_nop 0
	global_load_lds_dwordx4 v[154:155], off
	s_waitcnt vmcnt(6)
	s_barrier
	s_setprio 1
	v_mfma_f32_16x16x32_bf16 v[52:55], v[232:235], v[186:189], v[52:55]
	v_mfma_f32_16x16x32_bf16 v[48:51], v[240:243], v[186:189], v[48:51]
	v_mfma_f32_16x16x32_bf16 v[36:39], v[232:235], v[194:197], v[36:39]
	v_mfma_f32_16x16x32_bf16 v[32:35], v[240:243], v[194:197], v[32:35]
	v_mfma_f32_16x16x32_bf16 v[20:23], v[232:235], v[224:227], v[20:23]
	v_mfma_f32_16x16x32_bf16 v[16:19], v[240:243], v[224:227], v[16:19]
	v_mfma_f32_16x16x32_bf16 v[52:55], v[236:239], v[190:193], v[52:55]
	v_mfma_f32_16x16x32_bf16 v[48:51], v[244:247], v[190:193], v[48:51]
	v_mfma_f32_16x16x32_bf16 v[36:39], v[236:239], v[198:201], v[36:39]
	v_mfma_f32_16x16x32_bf16 v[32:35], v[244:247], v[198:201], v[32:35]
	v_mfma_f32_16x16x32_bf16 v[20:23], v[236:239], v[228:231], v[20:23]
	v_mfma_f32_16x16x32_bf16 v[16:19], v[244:247], v[228:231], v[16:19]
	s_setprio 0
	s_add_i32 s72, 0, 0x18000
	v_add_u32_e32 v96, s72, v163
	s_barrier
	ds_read_b128 v[154:157], v96
	ds_read_b128 v[170:173], v96 offset:1024
	ds_read_b128 v[174:177], v96 offset:2048
	ds_read_b128 v[182:185], v96 offset:3072
	s_add_u32 s60, s60, 0x30000
	s_addc_u32 s61, s61, 0
	s_mov_b32 m0, s37
	v_lshl_add_u64 v[232:233], s[60:61], 0, v[138:139]
	ds_read_b128 v[186:189], v168 offset:32768
	ds_read_b128 v[190:193], v168 offset:33792
	ds_read_b128 v[194:197], v168 offset:34816
	ds_read_b128 v[198:201], v168 offset:35840
	ds_read_b128 v[224:227], v168 offset:36864
	ds_read_b128 v[228:231], v168 offset:37888
	global_load_lds_dwordx4 v[232:233], off
	v_lshl_add_u64 v[232:233], s[60:61], 0, v[142:143]
	s_mov_b32 m0, s57
	s_mov_b64 exec, s[98:99]
	global_load_lds_dwordx4 v[232:233], off
	s_mov_b64 exec, -1
	s_waitcnt lgkmcnt(8)
	s_barrier
	s_waitcnt lgkmcnt(0)
	s_setprio 1
	s_waitcnt lgkmcnt(0)
	v_mfma_f32_16x16x32_bf16 v[134:137], v[154:157], v[186:189], v[134:137]
	v_mfma_f32_16x16x32_bf16 v[130:133], v[174:177], v[186:189], v[130:133]
	v_mfma_f32_16x16x32_bf16 v[92:95], v[154:157], v[194:197], v[92:95]
	v_mfma_f32_16x16x32_bf16 v[88:91], v[174:177], v[194:197], v[88:91]
	v_mfma_f32_16x16x32_bf16 v[76:79], v[154:157], v[224:227], v[76:79]
	v_mfma_f32_16x16x32_bf16 v[72:75], v[174:177], v[224:227], v[72:75]
	v_mfma_f32_16x16x32_bf16 v[134:137], v[170:173], v[190:193], v[134:137]
	v_mfma_f32_16x16x32_bf16 v[130:133], v[182:185], v[190:193], v[130:133]
	v_mfma_f32_16x16x32_bf16 v[92:95], v[170:173], v[198:201], v[92:95]
	v_mfma_f32_16x16x32_bf16 v[88:91], v[182:185], v[198:201], v[88:91]
	v_mfma_f32_16x16x32_bf16 v[76:79], v[170:173], v[228:231], v[76:79]
	v_mfma_f32_16x16x32_bf16 v[72:75], v[182:185], v[228:231], v[72:75]
	s_setprio 0
	s_barrier
	s_add_i32 s60, 0, 0x1c000
	s_add_i32 s61, s72, s18
	v_add_u32_e32 v96, s60, v163
	v_lshl_add_u64 v[160:161], v[160:161], 0, s[6:7]
	s_mov_b32 m0, s61
	ds_read_b128 v[232:235], v96
	ds_read_b128 v[236:239], v96 offset:1024
	ds_read_b128 v[240:243], v96 offset:2048
	ds_read_b128 v[244:247], v96 offset:3072
	global_load_lds_dwordx4 v[160:161], off
	v_lshl_add_u64 v[160:161], v[164:165], 0, s[6:7]
	s_add_i32 m0, s61, 0x2000
	s_nop 0
	global_load_lds_dwordx4 v[160:161], off
	s_barrier
	s_waitcnt lgkmcnt(0)
	s_setprio 1
	s_waitcnt lgkmcnt(0)
	v_mfma_f32_16x16x32_bf16 v[110:113], v[232:235], v[186:189], v[110:113]
	v_mfma_f32_16x16x32_bf16 v[98:101], v[240:243], v[186:189], v[98:101]
	v_mfma_f32_16x16x32_bf16 v[84:87], v[232:235], v[194:197], v[84:87]
	v_mfma_f32_16x16x32_bf16 v[80:83], v[240:243], v[194:197], v[80:83]
	v_mfma_f32_16x16x32_bf16 v[68:71], v[232:235], v[224:227], v[68:71]
	v_mfma_f32_16x16x32_bf16 v[64:67], v[240:243], v[224:227], v[64:67]
	v_mfma_f32_16x16x32_bf16 v[110:113], v[236:239], v[190:193], v[110:113]
	v_mfma_f32_16x16x32_bf16 v[98:101], v[244:247], v[190:193], v[98:101]
	v_mfma_f32_16x16x32_bf16 v[84:87], v[236:239], v[198:201], v[84:87]
	v_mfma_f32_16x16x32_bf16 v[80:83], v[244:247], v[198:201], v[80:83]
	v_mfma_f32_16x16x32_bf16 v[68:71], v[236:239], v[228:231], v[68:71]
	v_mfma_f32_16x16x32_bf16 v[64:67], v[244:247], v[228:231], v[64:67]
	s_setprio 0
	s_mov_b32 m0, s62
	v_lshl_add_u64 v[160:161], v[202:203], 0, s[6:7]
	s_barrier
	ds_read_b128 v[186:189], v168 offset:49152
	ds_read_b128 v[190:193], v168 offset:50176
	ds_read_b128 v[194:197], v168 offset:51200
	ds_read_b128 v[198:201], v168 offset:52224
	ds_read_b128 v[224:227], v168 offset:53248
	ds_read_b128 v[228:231], v168 offset:54272
	global_load_lds_dwordx4 v[160:161], off
	v_lshl_add_u64 v[160:161], v[248:249], 0, s[6:7]
	s_mov_b32 m0, s63
	s_mov_b64 exec, s[98:99]
	global_load_lds_dwordx4 v[160:161], off
	s_mov_b64 exec, -1
	s_barrier
	s_waitcnt lgkmcnt(0)
	s_setprio 1
	s_waitcnt lgkmcnt(0)
	v_mfma_f32_16x16x32_bf16 v[60:63], v[154:157], v[186:189], v[60:63]
	v_mfma_f32_16x16x32_bf16 v[56:59], v[174:177], v[186:189], v[56:59]
	v_mfma_f32_16x16x32_bf16 v[44:47], v[154:157], v[194:197], v[44:47]
	v_mfma_f32_16x16x32_bf16 v[40:43], v[174:177], v[194:197], v[40:43]
	v_mfma_f32_16x16x32_bf16 v[28:31], v[154:157], v[224:227], v[28:31]
	v_mfma_f32_16x16x32_bf16 v[24:27], v[174:177], v[224:227], v[24:27]
	v_mfma_f32_16x16x32_bf16 v[60:63], v[170:173], v[190:193], v[60:63]
	v_mfma_f32_16x16x32_bf16 v[56:59], v[182:185], v[190:193], v[56:59]
	v_mfma_f32_16x16x32_bf16 v[44:47], v[170:173], v[198:201], v[44:47]
	v_mfma_f32_16x16x32_bf16 v[40:43], v[182:185], v[198:201], v[40:43]
	v_mfma_f32_16x16x32_bf16 v[28:31], v[170:173], v[228:231], v[28:31]
	v_mfma_f32_16x16x32_bf16 v[24:27], v[182:185], v[228:231], v[24:27]
	s_setprio 0
	s_barrier
	s_add_u32 s58, s58, 0x40080
	s_addc_u32 s59, s59, 0
	s_add_i32 s60, s60, s18
	v_lshl_add_u64 v[154:155], s[58:59], 0, v[140:141]
	s_mov_b32 m0, s60
	s_nop 0
	global_load_lds_dwordx4 v[154:155], off
	v_lshl_add_u64 v[154:155], s[58:59], 0, v[144:145]
	s_add_i32 m0, s60, 0x2000
	s_nop 0
	global_load_lds_dwordx4 v[154:155], off
	s_waitcnt vmcnt(6)
	s_barrier
	s_setprio 1
	v_mfma_f32_16x16x32_bf16 v[52:55], v[232:235], v[186:189], v[52:55]
	v_mfma_f32_16x16x32_bf16 v[48:51], v[240:243], v[186:189], v[48:51]
	v_mfma_f32_16x16x32_bf16 v[36:39], v[232:235], v[194:197], v[36:39]
	v_mfma_f32_16x16x32_bf16 v[32:35], v[240:243], v[194:197], v[32:35]
	v_mfma_f32_16x16x32_bf16 v[20:23], v[232:235], v[224:227], v[20:23]
	v_mfma_f32_16x16x32_bf16 v[16:19], v[240:243], v[224:227], v[16:19]
	v_mfma_f32_16x16x32_bf16 v[52:55], v[236:239], v[190:193], v[52:55]
	v_mfma_f32_16x16x32_bf16 v[48:51], v[244:247], v[190:193], v[48:51]
	v_mfma_f32_16x16x32_bf16 v[36:39], v[236:239], v[198:201], v[36:39]
	v_mfma_f32_16x16x32_bf16 v[32:35], v[244:247], v[198:201], v[32:35]
	v_mfma_f32_16x16x32_bf16 v[20:23], v[236:239], v[228:231], v[20:23]
	v_mfma_f32_16x16x32_bf16 v[16:19], v[244:247], v[228:231], v[16:19]
	s_setprio 0
	s_add_i32 s71, s71, 2
	s_add_u32 s42, s42, 0x100
	s_addc_u32 s43, s43, 0
	s_add_u32 s69, s69, 0x100
	s_addc_u32 s70, s70, 0
	s_cmp_gt_u32 s71, 13
	s_barrier
	s_cbranch_scc0 .LBB0_465
	s_mul_i32 s42, s67, 0xc0
	s_add_i32 s42, s42, s19
	s_cmpk_lt_u32 s42, 0x2000
	s_cselect_b32 s43, 1, 2
	v_or_b32_e32 v156, s42, v159
	v_mov_b32_e32 v96, s43
	v_cmp_lt_i32_e32 vcc, s23, v156
	v_add_u32_e32 v160, 16, v156
	v_lshl_or_b32 v154, s56, 8, v166
	v_cndmask_b32_e32 v169, 0, v96, vcc
	s_waitcnt vmcnt(0)
	v_add_f32_e32 v96, v126, v127
	v_add_f32_e32 v126, v128, v129
	v_add_f32_e32 v96, v96, v126
	v_mov_b32_e32 v126, v96
	s_nop 1
	v_permlane16_swap_b32_e32 v96, v126
	v_add_f32_e32 v96, v96, v126
	v_mov_b32_e32 v126, v96
	s_nop 1
	v_permlane32_swap_b32_e32 v96, v126
	v_add_f32_e32 v96, v96, v126
	v_fmamk_f32 v96, v96, 0x3a800000, v207
	v_rsq_f32_e32 v162, v96
	v_add_f32_e32 v96, v122, v123
	v_add_f32_e32 v122, v124, v125
	v_add_f32_e32 v96, v96, v122
	v_mov_b32_e32 v122, v96
	s_nop 1
	v_permlane16_swap_b32_e32 v96, v122
	v_add_f32_e32 v96, v96, v122
	v_mov_b32_e32 v122, v96
	s_nop 1
	v_permlane32_swap_b32_e32 v96, v122
	v_add_f32_e32 v96, v96, v122
	v_fmamk_f32 v96, v96, 0x3a800000, v207
	v_rsq_f32_e32 v158, v96
	v_add_f32_e32 v96, v118, v119
	v_add_f32_e32 v118, v120, v121
	v_add_f32_e32 v96, v96, v118
	v_mov_b32_e32 v118, v96
	s_nop 1
	v_permlane16_swap_b32_e32 v96, v118
	v_add_f32_e32 v96, v96, v118
	v_mov_b32_e32 v118, v96
	s_nop 1
	v_permlane32_swap_b32_e32 v96, v118
	v_add_f32_e32 v96, v96, v118
	v_fmamk_f32 v96, v96, 0x3a800000, v207
	v_rsq_f32_e32 v128, v96
	v_add_f32_e32 v96, v114, v115
	v_add_f32_e32 v114, v116, v117
	v_add_f32_e32 v96, v96, v114
	v_mov_b32_e32 v114, v96
	s_nop 1
	v_permlane16_swap_b32_e32 v96, v114
	v_add_f32_e32 v96, v96, v114
	v_mov_b32_e32 v114, v96
	s_nop 1
	v_permlane32_swap_b32_e32 v96, v114
	v_add_f32_e32 v96, v96, v114
	v_fmamk_f32 v96, v96, 0x3a800000, v207
	v_rsq_f32_e32 v126, v96
	v_add_f32_e32 v96, v106, v107
	v_add_f32_e32 v106, v108, v109
	v_add_f32_e32 v96, v96, v106
	v_mov_b32_e32 v106, v96
	s_nop 1
	v_permlane16_swap_b32_e32 v96, v106
	v_add_f32_e32 v96, v96, v106
	v_mov_b32_e32 v106, v96
	s_nop 1
	v_permlane32_swap_b32_e32 v96, v106
	v_add_f32_e32 v96, v96, v106
	v_fmamk_f32 v96, v96, 0x3a800000, v207
	v_rsq_f32_e32 v124, v96
	v_add_f32_e32 v96, v102, v103
	v_add_f32_e32 v102, v104, v105
	v_add_f32_e32 v96, v96, v102
	v_mov_b32_e32 v102, v96
	s_nop 1
	v_permlane16_swap_b32_e32 v96, v102
	v_add_f32_e32 v96, v96, v102
	v_mov_b32_e32 v102, v96
	s_nop 1
	v_permlane32_swap_b32_e32 v96, v102
	v_add_f32_e32 v96, v96, v102
	v_fmamk_f32 v96, v96, 0x3a800000, v207
	v_rsq_f32_e32 v122, v96
	s_mov_b64 s[58:59], -1
	s_cmp_gt_i32 s56, 3
	v_ashrrev_i32_e32 v157, 31, v156
	v_cmp_lt_i32_e32 vcc, s26, v156
	v_cmp_gt_u32_e64 s[42:43], s24, v160
	s_cbranch_scc0 .LBB0_478
	v_lshlrev_b64 v[102:103], 11, v[156:157]
	v_lshl_add_u32 v96, s56, 7, v167
	v_lshl_add_u64 v[102:103], s[48:49], 0, v[102:103]
	v_lshl_add_u64 v[106:107], v[96:97], 1, v[102:103]
	v_pk_fma_f32 v[102:103], v[136:137], v[162:163], v[6:7] op_sel_hi:[1,0,1]
	v_pk_fma_f32 v[104:105], v[134:135], v[162:163], v[4:5] op_sel_hi:[1,0,1]
	v_pk_fma_f32 v[108:109], v[112:113], v[162:163], v[14:15] op_sel_hi:[1,0,1]
	v_pk_fma_f32 v[114:115], v[110:111], v[162:163], v[12:13] op_sel_hi:[1,0,1]
	v_pk_mul_f32 v[108:109], v[102:103], v[108:109]
	v_pk_mul_f32 v[102:103], v[104:105], v[114:115]
	v_pk_fma_f32 v[104:105], v[132:133], v[162:163], v[2:3] op_sel_hi:[1,0,1]
	v_pk_fma_f32 v[114:115], v[130:131], v[162:163], v[0:1] op_sel_hi:[1,0,1]
	v_pk_fma_f32 v[116:117], v[100:101], v[162:163], v[10:11] op_sel_hi:[1,0,1]
	v_pk_fma_f32 v[118:119], v[98:99], v[162:163], v[8:9] op_sel_hi:[1,0,1]
	v_pk_mul_f32 v[116:117], v[104:105], v[116:117]
	v_pk_mul_f32 v[104:105], v[114:115], v[118:119]
	v_cvt_pk_bf16_f32 v102, v102, v103
	v_cvt_pk_bf16_f32 v103, v108, v109
	v_mov_b64_e32 v[120:121], v[14:15]
	v_cvt_pk_bf16_f32 v104, v104, v105
	v_cvt_pk_bf16_f32 v105, v116, v117
	global_store_dwordx4 v[106:107], v[102:105], off
	v_mov_b64_e32 v[116:117], v[10:11]
	v_mov_b64_e32 v[108:109], v[6:7]
	v_cndmask_b32_e64 v102, 2, 1, s[42:43]
	v_cndmask_b32_e32 v125, 0, v102, vcc
	v_mov_b64_e32 v[104:105], v[2:3]
	v_mov_b32_e32 v155, v97
	v_cmp_ne_u32_e32 vcc, v125, v169
	v_mov_b64_e32 v[114:115], v[8:9]
	v_mov_b64_e32 v[102:103], v[0:1]
	v_mov_b64_e32 v[118:119], v[12:13]
	v_mov_b64_e32 v[106:107], v[4:5]
	v_mov_b32_e32 v123, v169
	s_and_saveexec_b64 s[42:43], vcc
	s_cbranch_execz .LBB0_469
	v_mul_u32_u24_e32 v102, 0x7600, v125
	v_lshlrev_b32_e32 v102, 2, v102
	v_mov_b32_e32 v103, v97
	v_lshl_add_u64 v[102:103], s[44:45], 0, v[102:103]
	v_lshl_add_u64 v[118:119], v[154:155], 2, v[102:103]
	global_load_dwordx4 v[102:105], v[118:119], off offset:16
	global_load_dwordx4 v[106:109], v[118:119], off
	global_load_dwordx4 v[114:117], v[118:119], off offset:528
	s_nop 0
	global_load_dwordx4 v[118:121], v[118:119], off offset:512
	v_mov_b32_e32 v123, v125

.LBB0_1021:
	s_add_i32 vcc_hi, s46, 2
	s_add_u32 s84, s44, 0x80
	s_addc_u32 s47, s45, 0
	s_add_i32 s29, 0, 0x10000
	v_add_u32_e32 v96, s29, v225
	ds_read_b128 v[56:59], v96
	ds_read_b128 v[68:71], v96 offset:1024
	ds_read_b128 v[80:83], v96 offset:2048
	ds_read_b128 v[98:101], v96 offset:3072
	s_cmp_eq_u32 s90, s46
	s_cselect_b32 s46, s80, s84
	s_cselect_b32 s47, s81, s47
	s_cselect_b32 s85, s83, vcc_lo
	s_cselect_b32 s84, s82, s87
	v_lshl_add_u64 v[106:107], s[44:45], 0, v[188:189]
	s_add_i32 m0, s2, 0xc000
	ds_read_b128 v[102:105], v227
	ds_read_b128 v[112:115], v227 offset:1024
	ds_read_b128 v[124:127], v227 offset:2048
	ds_read_b128 v[192:195], v227 offset:3072
	ds_read_b128 v[196:199], v227 offset:4096
	ds_read_b128 v[200:203], v227 offset:5120
	global_load_lds_dwordx4 v[106:107], off
	v_lshl_add_u64 v[106:107], s[44:45], 0, v[190:191]
	s_add_i32 m0, s2, 0xe000
	s_mov_b64 exec, s[98:99]
	global_load_lds_dwordx4 v[106:107], off
	s_mov_b64 exec, -1
	s_waitcnt lgkmcnt(8)
	s_barrier
	s_waitcnt lgkmcnt(0)
	s_setprio 1
	s_waitcnt lgkmcnt(0)
	v_mfma_f32_16x16x32_bf16 v[172:175], v[56:59], v[102:105], v[172:175]
	v_mfma_f32_16x16x32_bf16 v[168:171], v[80:83], v[102:105], v[168:171]
	v_mfma_f32_16x16x32_bf16 v[156:159], v[56:59], v[124:127], v[156:159]
	v_mfma_f32_16x16x32_bf16 v[152:155], v[80:83], v[124:127], v[152:155]
	v_mfma_f32_16x16x32_bf16 v[132:135], v[56:59], v[196:199], v[132:135]
	v_mfma_f32_16x16x32_bf16 v[128:131], v[80:83], v[196:199], v[128:131]
	v_mfma_f32_16x16x32_bf16 v[172:175], v[68:71], v[112:115], v[172:175]
	v_mfma_f32_16x16x32_bf16 v[168:171], v[98:101], v[112:115], v[168:171]
	v_mfma_f32_16x16x32_bf16 v[156:159], v[68:71], v[192:195], v[156:159]
	v_mfma_f32_16x16x32_bf16 v[152:155], v[98:101], v[192:195], v[152:155]
	v_mfma_f32_16x16x32_bf16 v[132:135], v[68:71], v[200:203], v[132:135]
	v_mfma_f32_16x16x32_bf16 v[128:131], v[98:101], v[200:203], v[128:131]
	s_setprio 0
	s_barrier
	s_add_i32 s96, 0, 0x14000
	s_add_i32 s29, s29, s18
	v_add_u32_e32 v96, s96, v225
	v_lshl_add_u64 v[106:107], s[84:85], 0, v[182:183]
	s_mov_b32 m0, s29
	ds_read_b128 v[228:231], v96
	ds_read_b128 v[232:235], v96 offset:1024
	ds_read_b128 v[236:239], v96 offset:2048
	ds_read_b128 v[240:243], v96 offset:3072
	global_load_lds_dwordx4 v[106:107], off
	v_lshl_add_u64 v[248:249], s[84:85], 0, v[186:187]
	s_add_i32 m0, s29, 0x2000
	s_nop 0
	global_load_lds_dwordx4 v[248:249], off
	s_barrier
	s_waitcnt lgkmcnt(0)
	s_setprio 1
	s_waitcnt lgkmcnt(0)
	v_mfma_f32_16x16x32_bf16 v[164:167], v[228:231], v[102:105], v[164:167]
	v_mfma_f32_16x16x32_bf16 v[102:105], v[236:239], v[102:105], v[160:163]
	v_mfma_f32_16x16x32_bf16 v[120:123], v[228:231], v[196:199], v[120:123]
	v_mfma_f32_16x16x32_bf16 v[116:119], v[236:239], v[196:199], v[116:119]
	v_mfma_f32_16x16x32_bf16 v[164:167], v[232:235], v[112:115], v[164:167]
	v_mfma_f32_16x16x32_bf16 v[102:105], v[240:243], v[112:115], v[102:105]
	v_mfma_f32_16x16x32_bf16 v[112:115], v[228:231], v[124:127], v[148:151]
	v_mfma_f32_16x16x32_bf16 v[124:127], v[236:239], v[124:127], v[144:147]
	v_mfma_f32_16x16x32_bf16 v[120:123], v[232:235], v[200:203], v[120:123]
	v_mfma_f32_16x16x32_bf16 v[116:119], v[240:243], v[200:203], v[116:119]
	v_mfma_f32_16x16x32_bf16 v[112:115], v[232:235], v[192:195], v[112:115]
	v_mfma_f32_16x16x32_bf16 v[124:127], v[240:243], v[192:195], v[124:127]
	s_setprio 0
	s_mov_b32 m0, s2
	v_lshl_add_u64 v[250:251], s[46:47], 0, v[176:177]
	s_barrier
	ds_read_b128 v[144:147], v227 offset:16384
	ds_read_b128 v[148:151], v227 offset:17408
	ds_read_b128 v[160:163], v227 offset:18432
	ds_read_b128 v[192:195], v227 offset:19456
	ds_read_b128 v[196:199], v227 offset:20480
	ds_read_b128 v[200:203], v227 offset:21504
	global_load_lds_dwordx4 v[250:251], off
	v_lshl_add_u64 v[252:253], s[46:47], 0, v[184:185]
	s_mov_b32 m0, s3
	s_mov_b64 exec, s[98:99]
	global_load_lds_dwordx4 v[252:253], off
	s_mov_b64 exec, -1
	s_barrier
	s_waitcnt lgkmcnt(0)
	s_setprio 1
	s_waitcnt lgkmcnt(0)
	v_mfma_f32_16x16x32_bf16 v[88:91], v[56:59], v[144:147], v[88:91]
	v_mfma_f32_16x16x32_bf16 v[84:87], v[80:83], v[144:147], v[84:87]
	v_mfma_f32_16x16x32_bf16 v[52:55], v[56:59], v[160:163], v[52:55]
	v_mfma_f32_16x16x32_bf16 v[48:51], v[80:83], v[160:163], v[48:51]
	v_mfma_f32_16x16x32_bf16 v[28:31], v[56:59], v[196:199], v[28:31]
	v_mfma_f32_16x16x32_bf16 v[24:27], v[80:83], v[196:199], v[24:27]
	v_mfma_f32_16x16x32_bf16 v[88:91], v[68:71], v[148:151], v[88:91]
	v_mfma_f32_16x16x32_bf16 v[84:87], v[98:101], v[148:151], v[84:87]
	v_mfma_f32_16x16x32_bf16 v[52:55], v[68:71], v[192:195], v[52:55]
	v_mfma_f32_16x16x32_bf16 v[48:51], v[98:101], v[192:195], v[48:51]
	v_mfma_f32_16x16x32_bf16 v[28:31], v[68:71], v[200:203], v[28:31]
	v_mfma_f32_16x16x32_bf16 v[24:27], v[98:101], v[200:203], v[24:27]
	s_setprio 0
	s_barrier
	s_add_u32 s84, s84, s57
	s_addc_u32 s85, s85, 0
	s_add_i32 s29, s96, s18
	v_lshl_add_u64 v[218:219], s[84:85], 0, v[182:183]
	s_mov_b32 m0, s29
	v_lshl_add_u64 v[220:221], s[84:85], 0, v[186:187]
	global_load_lds_dwordx4 v[218:219], off
	s_add_i32 m0, s29, 0x2000
	s_nop 0
	global_load_lds_dwordx4 v[220:221], off
	s_waitcnt vmcnt(6)
	s_barrier
	s_setprio 1
	v_mfma_f32_16x16x32_bf16 v[44:47], v[228:231], v[160:163], v[44:47]
	v_mfma_f32_16x16x32_bf16 v[40:43], v[236:239], v[160:163], v[40:43]
	v_mfma_f32_16x16x32_bf16 v[20:23], v[228:231], v[196:199], v[20:23]
	v_mfma_f32_16x16x32_bf16 v[16:19], v[236:239], v[196:199], v[16:19]
	v_mfma_f32_16x16x32_bf16 v[56:59], v[228:231], v[144:147], v[76:79]
	v_mfma_f32_16x16x32_bf16 v[68:71], v[236:239], v[144:147], v[72:75]
	v_mfma_f32_16x16x32_bf16 v[44:47], v[232:235], v[192:195], v[44:47]
	v_mfma_f32_16x16x32_bf16 v[40:43], v[240:243], v[192:195], v[40:43]
	v_mfma_f32_16x16x32_bf16 v[20:23], v[232:235], v[200:203], v[20:23]
	v_mfma_f32_16x16x32_bf16 v[16:19], v[240:243], v[200:203], v[16:19]
	v_mfma_f32_16x16x32_bf16 v[56:59], v[232:235], v[148:151], v[56:59]
	v_mfma_f32_16x16x32_bf16 v[68:71], v[240:243], v[148:151], v[68:71]
	s_setprio 0
	s_add_i32 s29, 0, 0x18000
	v_add_u32_e32 v96, s29, v225
	s_barrier
	ds_read_b128 v[72:75], v96
	ds_read_b128 v[76:79], v96 offset:1024
	ds_read_b128 v[80:83], v96 offset:2048
	ds_read_b128 v[98:101], v96 offset:3072
	s_add_u32 s46, s46, s64
	s_addc_u32 s47, s47, 0
	s_mov_b32 m0, s4
	v_lshl_add_u64 v[160:161], s[46:47], 0, v[176:177]
	ds_read_b128 v[144:147], v227 offset:32768
	ds_read_b128 v[148:151], v227 offset:33792
	ds_read_b128 v[192:195], v227 offset:34816
	ds_read_b128 v[196:199], v227 offset:35840
	ds_read_b128 v[200:203], v227 offset:36864
	ds_read_b128 v[228:231], v227 offset:37888
	global_load_lds_dwordx4 v[160:161], off
	v_lshl_add_u64 v[160:161], s[46:47], 0, v[184:185]
	s_mov_b32 m0, s5
	s_mov_b64 exec, s[98:99]
	global_load_lds_dwordx4 v[160:161], off
	s_mov_b64 exec, -1
	s_waitcnt lgkmcnt(8)
	s_barrier
	s_waitcnt lgkmcnt(0)
	s_setprio 1
	s_waitcnt lgkmcnt(0)
	v_mfma_f32_16x16x32_bf16 v[160:163], v[72:75], v[144:147], v[172:175]
	v_mfma_f32_16x16x32_bf16 v[172:175], v[76:79], v[148:151], v[160:163]
	v_mfma_f32_16x16x32_bf16 v[160:163], v[80:83], v[144:147], v[168:171]
	v_mfma_f32_16x16x32_bf16 v[156:159], v[72:75], v[192:195], v[156:159]
	v_mfma_f32_16x16x32_bf16 v[152:155], v[80:83], v[192:195], v[152:155]
	v_mfma_f32_16x16x32_bf16 v[132:135], v[72:75], v[200:203], v[132:135]
	v_mfma_f32_16x16x32_bf16 v[128:131], v[80:83], v[200:203], v[128:131]
	v_mfma_f32_16x16x32_bf16 v[168:171], v[98:101], v[148:151], v[160:163]
	v_mfma_f32_16x16x32_bf16 v[156:159], v[76:79], v[196:199], v[156:159]
	v_mfma_f32_16x16x32_bf16 v[152:155], v[98:101], v[196:199], v[152:155]
	v_mfma_f32_16x16x32_bf16 v[132:135], v[76:79], v[228:231], v[132:135]
	v_mfma_f32_16x16x32_bf16 v[128:131], v[98:101], v[228:231], v[128:131]
	s_setprio 0
	s_barrier
	s_add_i32 s46, 0, 0x1c000
	s_add_i32 s29, s29, s18
	v_add_u32_e32 v96, s46, v225
	v_lshl_add_u64 v[106:107], v[106:107], 0, s[6:7]
	s_mov_b32 m0, s29
	ds_read_b128 v[232:235], v96
	ds_read_b128 v[236:239], v96 offset:1024
	ds_read_b128 v[240:243], v96 offset:2048
	ds_read_b128 v[244:247], v96 offset:3072
	global_load_lds_dwordx4 v[106:107], off
	v_lshl_add_u64 v[106:107], v[248:249], 0, s[6:7]
	s_add_i32 m0, s29, 0x2000
	s_nop 0
	global_load_lds_dwordx4 v[106:107], off
	s_barrier
	s_waitcnt lgkmcnt(0)
	s_setprio 1
	s_waitcnt lgkmcnt(0)
	v_mfma_f32_16x16x32_bf16 v[160:163], v[232:235], v[144:147], v[164:167]
	v_mfma_f32_16x16x32_bf16 v[102:105], v[240:243], v[144:147], v[102:105]
	v_mfma_f32_16x16x32_bf16 v[164:167], v[236:239], v[148:151], v[160:163]
	v_mfma_f32_16x16x32_bf16 v[160:163], v[244:247], v[148:151], v[102:105]
	v_mfma_f32_16x16x32_bf16 v[102:105], v[232:235], v[192:195], v[112:115]
	v_mfma_f32_16x16x32_bf16 v[148:151], v[236:239], v[196:199], v[102:105]
	v_mfma_f32_16x16x32_bf16 v[102:105], v[240:243], v[192:195], v[124:127]
	v_mfma_f32_16x16x32_bf16 v[144:147], v[244:247], v[196:199], v[102:105]
	v_mfma_f32_16x16x32_bf16 v[102:105], v[232:235], v[200:203], v[120:123]
	v_mfma_f32_16x16x32_bf16 v[120:123], v[236:239], v[228:231], v[102:105]
	v_mfma_f32_16x16x32_bf16 v[102:105], v[240:243], v[200:203], v[116:119]
	v_mfma_f32_16x16x32_bf16 v[116:119], v[244:247], v[228:231], v[102:105]
	s_setprio 0
	s_mov_b32 m0, s88
	v_lshl_add_u64 v[106:107], v[250:251], 0, s[6:7]
	s_barrier
	s_nop 2
	ds_read_b128 v[102:105], v227 offset:49152
	ds_read_b128 v[112:115], v227 offset:50176
	ds_read_b128 v[124:127], v227 offset:51200
	ds_read_b128 v[192:195], v227 offset:52224
	ds_read_b128 v[196:199], v227 offset:53248
	ds_read_b128 v[200:203], v227 offset:54272
	global_load_lds_dwordx4 v[106:107], off
	v_lshl_add_u64 v[106:107], v[252:253], 0, s[6:7]
	s_mov_b32 m0, s89
	s_mov_b64 exec, s[98:99]
	global_load_lds_dwordx4 v[106:107], off
	s_mov_b64 exec, -1
	s_barrier
	s_waitcnt lgkmcnt(0)
	s_setprio 1
	s_waitcnt lgkmcnt(0)
	v_mfma_f32_16x16x32_bf16 v[88:91], v[72:75], v[102:105], v[88:91]
	v_mfma_f32_16x16x32_bf16 v[84:87], v[80:83], v[102:105], v[84:87]
	v_mfma_f32_16x16x32_bf16 v[52:55], v[72:75], v[124:127], v[52:55]
	v_mfma_f32_16x16x32_bf16 v[48:51], v[80:83], v[124:127], v[48:51]
	v_mfma_f32_16x16x32_bf16 v[28:31], v[72:75], v[196:199], v[28:31]
	v_mfma_f32_16x16x32_bf16 v[24:27], v[80:83], v[196:199], v[24:27]
	v_mfma_f32_16x16x32_bf16 v[88:91], v[76:79], v[112:115], v[88:91]
	v_mfma_f32_16x16x32_bf16 v[84:87], v[98:101], v[112:115], v[84:87]
	v_mfma_f32_16x16x32_bf16 v[52:55], v[76:79], v[192:195], v[52:55]
	v_mfma_f32_16x16x32_bf16 v[48:51], v[98:101], v[192:195], v[48:51]
	v_mfma_f32_16x16x32_bf16 v[28:31], v[76:79], v[200:203], v[28:31]
	v_mfma_f32_16x16x32_bf16 v[24:27], v[98:101], v[200:203], v[24:27]
	s_setprio 0
	s_barrier
	s_add_i32 s29, s46, s18
	v_lshl_add_u64 v[72:73], v[218:219], 0, s[6:7]
	s_mov_b32 m0, s29
	s_nop 0
	global_load_lds_dwordx4 v[72:73], off
	v_lshl_add_u64 v[72:73], v[220:221], 0, s[6:7]
	s_add_i32 m0, s29, 0x2000
	s_nop 0
	global_load_lds_dwordx4 v[72:73], off
	s_waitcnt vmcnt(6)
	s_barrier
	s_setprio 1
	v_mfma_f32_16x16x32_bf16 v[56:59], v[232:235], v[102:105], v[56:59]
	v_mfma_f32_16x16x32_bf16 v[76:79], v[236:239], v[112:115], v[56:59]
	v_mfma_f32_16x16x32_bf16 v[56:59], v[240:243], v[102:105], v[68:71]
	v_mfma_f32_16x16x32_bf16 v[44:47], v[232:235], v[124:127], v[44:47]
	v_mfma_f32_16x16x32_bf16 v[40:43], v[240:243], v[124:127], v[40:43]
	v_mfma_f32_16x16x32_bf16 v[20:23], v[232:235], v[196:199], v[20:23]
	v_mfma_f32_16x16x32_bf16 v[16:19], v[240:243], v[196:199], v[16:19]
	v_mfma_f32_16x16x32_bf16 v[72:75], v[244:247], v[112:115], v[56:59]
	v_mfma_f32_16x16x32_bf16 v[44:47], v[236:239], v[192:195], v[44:47]
	v_mfma_f32_16x16x32_bf16 v[40:43], v[244:247], v[192:195], v[40:43]
	v_mfma_f32_16x16x32_bf16 v[20:23], v[236:239], v[200:203], v[20:23]
	v_mfma_f32_16x16x32_bf16 v[16:19], v[244:247], v[200:203], v[16:19]
	s_setprio 0
	s_add_u32 s44, s44, 0x100
	s_addc_u32 s45, s45, 0
	s_add_u32 s87, s87, 0x100
	s_addc_u32 vcc_lo, vcc_lo, 0
	s_cmp_ge_u32 vcc_hi, s37
	s_mov_b32 s46, vcc_hi
	s_barrier
	s_cbranch_scc0 .LBB0_1021
	s_mul_i32 s44, s86, 0xc0
	s_add_i32 s44, s44, s19
	s_cmpk_lt_u32 s44, 0x2000
	v_or_b32_e32 v198, s44, v223
	s_cselect_b32 s44, 1, 2
	v_mov_b32_e32 v56, s44
	v_cmp_lt_i32_e32 vcc, s23, v198
	v_lshl_or_b32 v192, s72, 8, v226
	v_ashrrev_i32_e32 v193, 31, v192
	v_cndmask_b32_e32 v228, 0, v56, vcc
	v_mul_u32_u24_e32 v56, 0x1800, v228
	v_lshlrev_b32_e32 v96, 2, v56
	v_lshl_add_u64 v[56:57], s[70:71], 0, v[96:97]
	v_lshlrev_b64 v[68:69], 2, v[192:193]
	v_lshl_add_u64 v[124:125], v[56:57], 0, v[68:69]
	global_load_dwordx4 v[56:59], v[124:125], off
	v_cndmask_b32_e64 v70, 0, 1, s[78:79]
	v_cmp_ne_u32_e64 s[46:47], 1, v70
	s_andn2_b64 vcc, exec, s[78:79]
	v_lshl_add_u64 v[196:197], s[54:55], 0, v[68:69]
	s_cbranch_vccnz .LBB0_1024
	global_load_dwordx4 v[80:83], v[196:197], off
	s_waitcnt vmcnt(0)
	v_pk_mul_f32 v[58:59], v[58:59], v[82:83]
	v_pk_mul_f32 v[56:57], v[56:57], v[80:81]

	.amdhsa_kernel _Z14fwd_megakernel6Params
		.amdhsa_group_segment_fixed_size 0
		.amdhsa_private_segment_fixed_size 0
		.amdhsa_kernarg_size 456
		.amdhsa_user_sgpr_count 2
		.amdhsa_user_sgpr_dispatch_ptr 0
		.amdhsa_user_sgpr_queue_ptr 0
		.amdhsa_user_sgpr_kernarg_segment_ptr 1
		.amdhsa_user_sgpr_dispatch_id 0
		.amdhsa_user_sgpr_kernarg_preload_length 0
		.amdhsa_user_sgpr_kernarg_preload_offset 0
		.amdhsa_user_sgpr_private_segment_size 0
		.amdhsa_uses_dynamic_stack 0
		.amdhsa_enable_private_segment 0
		.amdhsa_system_sgpr_workgroup_id_x 1
		.amdhsa_system_sgpr_workgroup_id_y 0
		.amdhsa_system_sgpr_workgroup_id_z 0
		.amdhsa_system_sgpr_workgroup_info 0
		.amdhsa_system_vgpr_workitem_id 2
		.amdhsa_next_free_vgpr 256
		.amdhsa_next_free_sgpr 100
		.amdhsa_accum_offset 256
		.amdhsa_reserve_vcc 1
		.amdhsa_float_round_mode_32 0
		.amdhsa_float_round_mode_16_64 0
		.amdhsa_float_denorm_mode_32 3
		.amdhsa_float_denorm_mode_16_64 3
		.amdhsa_dx10_clamp 1
		.amdhsa_ieee_mode 1
		.amdhsa_fp16_overflow 0
		.amdhsa_tg_split 0
		.amdhsa_exception_fp_ieee_invalid_op 0
		.amdhsa_exception_fp_denorm_src 0
		.amdhsa_exception_fp_ieee_div_zero 0
		.amdhsa_exception_fp_ieee_overflow 0
		.amdhsa_exception_fp_ieee_underflow 0
		.amdhsa_exception_fp_ieee_inexact 0
		.amdhsa_exception_int_div_zero 0
	.end_amdhsa_kernel

amdhsa.kernels:
  - .agpr_count:     0
    .args:
      - .offset:         0
        .size:           200
        .value_kind:     by_value
      - .offset:         200
        .size:           4
        .value_kind:     hidden_block_count_x
      - .offset:         204
        .size:           4
        .value_kind:     hidden_block_count_y
      - .offset:         208
        .size:           4
        .value_kind:     hidden_block_count_z
      - .offset:         212
        .size:           2
        .value_kind:     hidden_group_size_x
      - .offset:         214
        .size:           2
        .value_kind:     hidden_group_size_y
      - .offset:         216
        .size:           2
        .value_kind:     hidden_group_size_z
      - .offset:         218
        .size:           2
        .value_kind:     hidden_remainder_x
      - .offset:         220
        .size:           2
        .value_kind:     hidden_remainder_y
      - .offset:         222
        .size:           2
        .value_kind:     hidden_remainder_z
      - .offset:         240
        .size:           8
        .value_kind:     hidden_global_offset_x
      - .offset:         248
        .size:           8
        .value_kind:     hidden_global_offset_y
      - .offset:         256
        .size:           8
        .value_kind:     hidden_global_offset_z
      - .offset:         264
        .size:           2
        .value_kind:     hidden_grid_dims
      - .offset:         288
        .size:           8
        .value_kind:     hidden_multigrid_sync_arg
      - .offset:         320
        .size:           4
        .value_kind:     hidden_dynamic_lds_size
    .group_segment_fixed_size: 0
    .kernarg_segment_align: 8
    .kernarg_segment_size: 456
    .language:       OpenCL C
    .language_version:
      - 2
      - 0
    .max_flat_workgroup_size: 512
    .name:           _Z14fwd_megakernel6Params
    .private_segment_fixed_size: 0
    .sgpr_count:     106
    .sgpr_spill_count: 124
    .symbol:         _Z14fwd_megakernel6Params.kd
    .uniform_work_group_size: 1
    .uses_dynamic_stack: false
    .vgpr_count:     256
    .vgpr_spill_count: 0
    .wavefront_size: 64
